# weight convert split, larger deferred set: weights first read after SCAN_C (c_out, w1[2], w2[2], and all layer-3 weights) converted by the idle workgroups during SCAN_C
# speedup vs baseline: 1.0086x; 1.0043x over previous
; DI u16 f2bf(float x) { return (u16)(pk2bf(x, 0.f) & 0xffffu); }
; #define WSEL(i) if (t >= wTileStart(i)) { K = cK[i]; N = cN[i]; base = wTileStart(i); off = wOff(i); soff = cSrcOff[i]; bi = cBase[i]; }
; #define CVT_LOAD(C, V) { _Pragma("unroll") for (int i = 0; i < 4; ++i) { const int n_ = (C).n0 + tx * 4; \
;     V[i] = (n_ < (C).N) ? *(const float4*)((C).src + (size_t)((C).k0 + ty + 16 * i) * (C).N + n_) : make_float4(0.f, 0.f, 0.f, 0.f); } }
; DI CvtTile cvt_locate(const Ctx& p, int t) {
;   int K = cK[0], N = cN[0], base = 0; unsigned off = 0, soff = 0; int bi = 0;
;     ...
;   WSEL(1) WSEL(2) WSEL(3) WSEL(4) WSEL(5) WSEL(6) WSEL(7) WSEL(8) WSEL(9) WSEL(10) WSEL(11) WSEL(12) WSEL(13) WSEL(14) WSEL(15)
;     ...
;   const float* src = p.wbase[0];
; #pragma unroll
;   for (int q = 1; q < 8; ++q) if (bi == q) src = p.wbase[q];
;   const int lt = t - base, nkt = K / 64;
;   CvtTile c; c.src = src + soff; c.K = K; c.N = N; c.k0 = (lt % nkt) * 64; c.n0 = (lt / nkt) * 64; c.off = off;
;   return c;
; }
; DI void phase_convert(int wv_, int vb_, int nvb_, char* ws_, const Ctx& p, char* smem) {
;   float* tile = (float*)smem;
;   const int tid = tidx(wv_);
;   const int ty = tid >> 4, tx = tid & 15;
;   constexpr int total = wTileStart(16);
;   const int trips_ = (total + nvb_ - 1) / nvb_;
;     ...
;   CvtTile cur = cvt_locate(p, (vb_ < total) ? vb_ : total - 1);
;   float4 v[4];
;   CVT_LOAD(cur, v)
;   for (int k_ = 0; k_ < trips_; ++k_) {
;     const int tn = vb_ + (k_ + 1) * nvb_;
;     const CvtTile nxt = cvt_locate(p, (tn < total) ? tn : total - 1);
;     float4 vn[4];
;     CVT_LOAD(nxt, vn)
; #pragma unroll
;     for (int i = 0; i < 4; ++i) { float* d = tile + (ty + 16 * i) * 65 + tx * 4; d[0] = v[i].x; d[1] = v[i].y; d[2] = v[i].z; d[3] = v[i].w; }
;     __syncthreads();
;     {
;       const int n = tid >> 2, kq = tid & 3;
;       bf16x8 o0, o1;
; #pragma unroll
;       for (int j = 0; j < 8; ++j) { o0[j] = (short)f2bf(tile[(kq * 16 + j) * 65 + n]); o1[j] = (short)f2bf(tile[(kq * 16 + 8 + j) * 65 + n]); }
;       u16* dst = (u16*)(ws_ + WS_WT) + (size_t)cur.off + (size_t)(cur.n0 + n) * cur.K + cur.k0 + kq * 16;
;       *(bf16x8*)dst = o0; *(bf16x8*)(dst + 8) = o1;
;     }
;     __syncthreads();
.Lcvt_late_chk:
	s_nop 0
	s_nop 0
	s_nop 0
	s_nop 0
	s_nop 0
	s_nop 0
	s_nop 0
	s_nop 0
	s_nop 0
	s_nop 0
	s_nop 0
	s_nop 0
	s_nop 0
	s_nop 0
	s_nop 0
	v_readlane_b32 s0, v254, 14
	s_cmp_lt_u32 s0, 0x80
	s_cbranch_scc1 .LBB0_235
	s_mov_b64 s[56:57], s[54:55]
	v_readlane_b32 s54, v254, 46
	v_readlane_b32 s55, v254, 47
	v_readlane_b32 s44, v254, 14
	v_readlane_b32 s35, v254, 56
	s_sub_i32 s44, s44, 128
	s_sub_i32 s35, s35, 128
	s_mov_b32 s10, s33
	v_lshl_add_u32 v81, s10, 6, v204
	v_lshrrev_b32_e32 v74, 4, v81
	v_and_b32_e32 v75, 15, v81
	v_lshlrev_b32_e32 v75, 2, v75
	v_lshrrev_b32_e32 v78, 2, v81
	v_and_b32_e32 v79, 3, v81
	v_mul_u32_u24_e32 v76, 65, v74
	v_add_u32_e32 v76, v76, v75
	v_lshl_add_u32 v76, v76, 2, v214
	v_mul_u32_u24_e32 v77, 0x410, v79
	v_add_u32_e32 v77, v77, v78
	v_lshl_add_u32 v77, v77, 2, v214
	v_lshlrev_b32_e32 v79, 5, v79
	s_mov_b32 s34, 0
.Lcvtb_loop:
	s_mul_i32 s52, s34, s35
	s_add_i32 s52, s52, s44
	s_min_u32 s52, s52, 0x15ff
	s_mov_b32 s0, 4
	s_mov_b32 s1, 0x1200
	s_mov_b32 s2, 0
	s_mov_b32 s3, 0x480000
	s_mov_b32 s7, 0x480000
	s_mov_b32 s11, 0
	s_cmp_ge_u32 s52, 0x480
	s_cselect_b32 s0, 3, s0
	s_cselect_b32 s1, 0x400, s1
	s_cselect_b32 s2, 1, s2
	s_cselect_b32 s3, 0x80000, s3
	s_cselect_b32 s7, 0x980000, s7
	s_cselect_b32 s11, 0x480, s11
	s_cmp_ge_u32 s52, 0x500
	s_cselect_b32 s0, 4, s0
	s_cselect_b32 s1, 0x400, s1
	s_cselect_b32 s2, 5, s2
	s_cselect_b32 s3, 0, s3
	s_cselect_b32 s7, 0x1180000, s7
	s_cselect_b32 s11, 0x500, s11
	s_cmp_ge_u32 s52, 0x600
	s_cselect_b32 s0, 4, s0
	s_cselect_b32 s1, 0x1000, s1
	s_cselect_b32 s2, 6, s2
	s_cselect_b32 s3, 0x800000, s3
	s_cselect_b32 s7, 0x1a80000, s7
	s_cselect_b32 s11, 0x600, s11
	s_cmp_ge_u32 s52, 0xa00
	s_cselect_b32 s0, 4, s0
	s_cselect_b32 s1, 0x1000, s1
	s_cselect_b32 s2, 6, s2
	s_cselect_b32 s3, 0xc00000, s3
	s_cselect_b32 s7, 0x1e80000, s7
	s_cselect_b32 s11, 0xa00, s11
	s_cmp_ge_u32 s52, 0xe00
	s_cselect_b32 s0, 6, s0
	s_cselect_b32 s1, 0x400, s1
	s_cselect_b32 s2, 7, s2
	s_cselect_b32 s3, 0x800000, s3
	s_cselect_b32 s7, 0x2a80000, s7
	s_cselect_b32 s11, 0xe00, s11
	s_cmp_ge_u32 s52, 0x1200
	s_cselect_b32 s0, 6, s0
	s_cselect_b32 s1, 0x400, s1
	s_cselect_b32 s2, 7, s2
	s_cselect_b32 s3, 0xc00000, s3
	s_cselect_b32 s7, 0x2e80000, s7
	s_cselect_b32 s11, 0x1200, s11
	s_lshl_b32 s15, s2, 3
	s_add_i32 s15, s15, 0x60
	s_load_dwordx2 s[18:19], s[54:55], s15
	s_sub_i32 s15, s52, s11
	s_lshl_b32 s2, 1, s0
	s_add_i32 s2, s2, -1
	s_and_b32 s2, s15, s2
	s_lshl_b32 s2, s2, 6
	s_lshr_b32 s15, s15, s0
	s_lshl_b32 s15, s15, 6
	s_mov_b32 s6, s0
	s_add_i32 s11, s0, 6
	s_lshl_b32 s11, s15, s11
	s_add_i32 s11, s11, s7
	s_add_i32 s11, s11, s2
	s_lshl_b32 s11, s11, 1
	s_add_u32 s4, s78, s11
	s_addc_u32 s5, s79, 0
	s_mul_i32 s7, s2, s1
	s_add_i32 s7, s7, s3
	s_add_i32 s7, s7, s15
	s_lshl_b32 s7, s7, 2
	s_lshl_b32 s3, s1, 6
	v_mul_u32_u24_e32 v81, s1, v74
	v_add_u32_e32 v81, v81, v75
	v_lshlrev_b32_e32 v80, 2, v81
	v_add_u32_e32 v81, s15, v75
	v_mov_b32_e32 v2, 0
	v_mov_b32_e32 v3, 0
	v_mov_b32_e32 v4, 0
	v_mov_b32_e32 v5, 0
	v_mov_b32_e32 v6, 0
	v_mov_b32_e32 v7, 0
	v_mov_b32_e32 v8, 0
	v_mov_b32_e32 v9, 0
	v_mov_b32_e32 v10, 0
	v_mov_b32_e32 v11, 0
	v_mov_b32_e32 v12, 0
	v_mov_b32_e32 v13, 0
	v_mov_b32_e32 v14, 0
	v_mov_b32_e32 v15, 0
	v_mov_b32_e32 v16, 0
	v_mov_b32_e32 v17, 0
	s_waitcnt lgkmcnt(0)
	s_add_u32 s18, s18, s7
	s_addc_u32 s19, s19, 0
	v_cmp_gt_u32_e32 vcc, s1, v81
	s_and_saveexec_b64 s[100:101], vcc
	global_load_dwordx4 v[2:5], v80, s[18:19]
	s_add_u32 s18, s18, s3
	s_addc_u32 s19, s19, 0
	global_load_dwordx4 v[6:9], v80, s[18:19]
	s_add_u32 s18, s18, s3
	s_addc_u32 s19, s19, 0
	global_load_dwordx4 v[10:13], v80, s[18:19]
	s_add_u32 s18, s18, s3
	s_addc_u32 s19, s19, 0
	global_load_dwordx4 v[14:17], v80, s[18:19]
	s_mov_b64 exec, s[100:101]
	s_waitcnt vmcnt(0)
	ds_write_b32 v76, v2
	ds_write_b32 v76, v3 offset:4
	ds_write_b32 v76, v4 offset:8
	ds_write_b32 v76, v5 offset:12
	ds_write_b32 v76, v6 offset:4160
	ds_write_b32 v76, v7 offset:4164
	ds_write_b32 v76, v8 offset:4168
	ds_write_b32 v76, v9 offset:4172
	ds_write_b32 v76, v10 offset:8320
	ds_write_b32 v76, v11 offset:8324
	ds_write_b32 v76, v12 offset:8328
	ds_write_b32 v76, v13 offset:8332
	ds_write_b32 v76, v14 offset:12480
	ds_write_b32 v76, v15 offset:12484
	ds_write_b32 v76, v16 offset:12488
	ds_write_b32 v76, v17 offset:12492
	s_waitcnt lgkmcnt(0)
	s_barrier
	ds_read_b32 v50, v77
	ds_read_b32 v51, v77 offset:260
	ds_read_b32 v52, v77 offset:520
	ds_read_b32 v53, v77 offset:780
	ds_read_b32 v54, v77 offset:1040
	ds_read_b32 v55, v77 offset:1300
	ds_read_b32 v56, v77 offset:1560
	ds_read_b32 v57, v77 offset:1820
	ds_read_b32 v58, v77 offset:2080
	ds_read_b32 v59, v77 offset:2340
	ds_read_b32 v60, v77 offset:2600
	ds_read_b32 v61, v77 offset:2860
	ds_read_b32 v62, v77 offset:3120
	ds_read_b32 v63, v77 offset:3380
	ds_read_b32 v64, v77 offset:3640
	ds_read_b32 v65, v77 offset:3900
	s_add_i32 s15, s6, 7
	v_lshlrev_b32_e32 v82, s15, v78
	v_add_u32_e32 v82, v82, v79
	s_waitcnt lgkmcnt(0)
	v_cvt_pk_bf16_f32 v66, v50, v51
	v_cvt_pk_bf16_f32 v67, v52, v53
	v_cvt_pk_bf16_f32 v68, v54, v55
	v_cvt_pk_bf16_f32 v69, v56, v57
	v_cvt_pk_bf16_f32 v70, v58, v59
	v_cvt_pk_bf16_f32 v71, v60, v61
	v_cvt_pk_bf16_f32 v72, v62, v63
	v_cvt_pk_bf16_f32 v73, v64, v65
	global_store_dwordx4 v82, v[66:69], s[4:5]
	global_store_dwordx4 v82, v[70:73], s[4:5] offset:16
	s_barrier
	s_add_i32 s34, s34, 1
	s_mul_i32 s15, s34, s35
	s_cmp_lt_u32 s15, 0x1600
	s_cbranch_scc1 .Lcvtb_loop
	s_waitcnt vmcnt(0)
	s_mov_b64 s[54:55], s[56:57]
	s_mov_b32 s52, 0x6600000

; DI u16 f2bf(float x) { return (u16)(pk2bf(x, 0.f) & 0xffffu); }
; #define WSEL(i) if (t >= wTileStart(i)) { K = cK[i]; N = cN[i]; base = wTileStart(i); off = wOff(i); soff = cSrcOff[i]; bi = cBase[i]; }
; #define CVT_LOAD(C, V) { _Pragma("unroll") for (int i = 0; i < 4; ++i) { const int n_ = (C).n0 + tx * 4; \
;     V[i] = (n_ < (C).N) ? *(const float4*)((C).src + (size_t)((C).k0 + ty + 16 * i) * (C).N + n_) : make_float4(0.f, 0.f, 0.f, 0.f); } }
; DI CvtTile cvt_locate(const Ctx& p, int t) {
;   int K = cK[0], N = cN[0], base = 0; unsigned off = 0, soff = 0; int bi = 0;
;     ...
;   WSEL(1) WSEL(2) WSEL(3) WSEL(4) WSEL(5) WSEL(6) WSEL(7) WSEL(8) WSEL(9) WSEL(10) WSEL(11) WSEL(12) WSEL(13) WSEL(14) WSEL(15)
;     ...
;   const float* src = p.wbase[0];
; #pragma unroll
;   for (int q = 1; q < 8; ++q) if (bi == q) src = p.wbase[q];
;   const int lt = t - base, nkt = K / 64;
;   CvtTile c; c.src = src + soff; c.K = K; c.N = N; c.k0 = (lt % nkt) * 64; c.n0 = (lt / nkt) * 64; c.off = off;
;   return c;
; }
; DI void phase_convert(int wv_, int vb_, int nvb_, char* ws_, const Ctx& p, char* smem) {
;   float* tile = (float*)smem;
;   const int tid = tidx(wv_);
;   const int ty = tid >> 4, tx = tid & 15;
;   constexpr int total = wTileStart(16);
;   const int trips_ = (total + nvb_ - 1) / nvb_;
;     ...
;   CvtTile cur = cvt_locate(p, (vb_ < total) ? vb_ : total - 1);
;   float4 v[4];
;   CVT_LOAD(cur, v)
;   for (int k_ = 0; k_ < trips_; ++k_) {
;     const int tn = vb_ + (k_ + 1) * nvb_;
;     const CvtTile nxt = cvt_locate(p, (tn < total) ? tn : total - 1);
;     float4 vn[4];
;     CVT_LOAD(nxt, vn)
; #pragma unroll
;     for (int i = 0; i < 4; ++i) { float* d = tile + (ty + 16 * i) * 65 + tx * 4; d[0] = v[i].x; d[1] = v[i].y; d[2] = v[i].z; d[3] = v[i].w; }
;     __syncthreads();
;     {
;       const int n = tid >> 2, kq = tid & 3;
;       bf16x8 o0, o1;
; #pragma unroll
;       for (int j = 0; j < 8; ++j) { o0[j] = (short)f2bf(tile[(kq * 16 + j) * 65 + n]); o1[j] = (short)f2bf(tile[(kq * 16 + 8 + j) * 65 + n]); }
;       u16* dst = (u16*)(ws_ + WS_WT) + (size_t)cur.off + (size_t)(cur.n0 + n) * cur.K + cur.k0 + kq * 16;
;       *(bf16x8*)dst = o0; *(bf16x8*)(dst + 8) = o1;
;     }
;     __syncthreads();
.Lcvta_loop:
	s_mul_i32 s52, s34, s35
	s_add_i32 s52, s52, s44
	s_min_u32 s52, s52, 0x1c7f
	s_mov_b32 s0, 4
	s_mov_b32 s1, 0x1200
	s_mov_b32 s2, 0
	s_mov_b32 s3, 0
	s_mov_b32 s7, 0
	s_mov_b32 s11, 0
	s_cmp_ge_u32 s52, 0x480
	s_cselect_b32 s0, 3, s0
	s_cselect_b32 s1, 0x400, s1
	s_cselect_b32 s2, 1, s2
	s_cselect_b32 s3, 0, s3
	s_cselect_b32 s7, 0x900000, s7
	s_cselect_b32 s11, 0x480, s11
	s_cmp_ge_u32 s52, 0x500
	s_cselect_b32 s0, 4, s0
	s_cselect_b32 s1, 0x848, s1
	s_cselect_b32 s2, 2, s2
	s_cselect_b32 s3, 0, s3
	s_cselect_b32 s7, 0xa00000, s7
	s_cselect_b32 s11, 0x500, s11
	s_cmp_ge_u32 s52, 0x740
	s_cselect_b32 s0, 4, s0
	s_cselect_b32 s1, 0x400, s1
	s_cselect_b32 s2, 3, s2
	s_cselect_b32 s3, 0, s3
	s_cselect_b32 s7, 0xc40000, s7
	s_cselect_b32 s11, 0x740, s11
	s_cmp_ge_u32 s52, 0x840
	s_cselect_b32 s0, 4, s0
	s_cselect_b32 s1, 0x1010, s1
	s_cselect_b32 s2, 4, s2
	s_cselect_b32 s3, 0, s3
	s_cselect_b32 s7, 0xd40000, s7
	s_cselect_b32 s11, 0x840, s11
	s_cmp_ge_u32 s52, 0xc80
	s_cselect_b32 s0, 4, s0
	s_cselect_b32 s1, 0x1000, s1
	s_cselect_b32 s2, 6, s2
	s_cselect_b32 s3, 0, s3
	s_cselect_b32 s7, 0x1280000, s7
	s_cselect_b32 s11, 0xc80, s11
	s_cmp_ge_u32 s52, 0x1080
	s_cselect_b32 s0, 4, s0
	s_cselect_b32 s1, 0x1000, s1
	s_cselect_b32 s2, 6, s2
	s_cselect_b32 s3, 0x400000, s3
	s_cselect_b32 s7, 0x1680000, s7
	s_cselect_b32 s11, 0x1080, s11
	s_cmp_ge_u32 s52, 0x1480
	s_cselect_b32 s0, 6, s0
	s_cselect_b32 s1, 0x400, s1
	s_cselect_b32 s2, 7, s2
	s_cselect_b32 s3, 0, s3
	s_cselect_b32 s7, 0x2280000, s7
	s_cselect_b32 s11, 0x1480, s11
	s_cmp_ge_u32 s52, 0x1880
	s_cselect_b32 s0, 6, s0
	s_cselect_b32 s1, 0x400, s1
	s_cselect_b32 s2, 7, s2
	s_cselect_b32 s3, 0x400000, s3
	s_cselect_b32 s7, 0x2680000, s7
	s_cselect_b32 s11, 0x1880, s11
	s_lshl_b32 s15, s2, 3
	s_add_i32 s15, s15, 0x60
	s_load_dwordx2 s[18:19], s[54:55], s15
	s_sub_i32 s15, s52, s11
	s_lshl_b32 s2, 1, s0
	s_add_i32 s2, s2, -1
	s_and_b32 s2, s15, s2
	s_lshl_b32 s2, s2, 6
	s_lshr_b32 s15, s15, s0
	s_lshl_b32 s15, s15, 6
	s_mov_b32 s6, s0
	s_add_i32 s11, s0, 6
	s_lshl_b32 s11, s15, s11
	s_add_i32 s11, s11, s7
	s_add_i32 s11, s11, s2
	s_lshl_b32 s11, s11, 1
	s_add_u32 s4, s78, s11
	s_addc_u32 s5, s79, 0
	s_mul_i32 s7, s2, s1
	s_add_i32 s7, s7, s3
	s_add_i32 s7, s7, s15
	s_lshl_b32 s7, s7, 2
	s_lshl_b32 s3, s1, 6
	v_mul_u32_u24_e32 v81, s1, v74
	v_add_u32_e32 v81, v81, v75
	v_lshlrev_b32_e32 v80, 2, v81
	v_add_u32_e32 v81, s15, v75
	v_mov_b32_e32 v2, 0
	v_mov_b32_e32 v3, 0
	v_mov_b32_e32 v4, 0
	v_mov_b32_e32 v5, 0
	v_mov_b32_e32 v6, 0
	v_mov_b32_e32 v7, 0
	v_mov_b32_e32 v8, 0
	v_mov_b32_e32 v9, 0
	v_mov_b32_e32 v10, 0
	v_mov_b32_e32 v11, 0
	v_mov_b32_e32 v12, 0
	v_mov_b32_e32 v13, 0
	v_mov_b32_e32 v14, 0
	v_mov_b32_e32 v15, 0
	v_mov_b32_e32 v16, 0
	v_mov_b32_e32 v17, 0
	s_waitcnt lgkmcnt(0)
	s_add_u32 s18, s18, s7
	s_addc_u32 s19, s19, 0
	v_cmp_gt_u32_e32 vcc, s1, v81
	s_and_saveexec_b64 s[100:101], vcc
	global_load_dwordx4 v[2:5], v80, s[18:19]
	s_add_u32 s18, s18, s3
	s_addc_u32 s19, s19, 0
	global_load_dwordx4 v[6:9], v80, s[18:19]
	s_add_u32 s18, s18, s3
	s_addc_u32 s19, s19, 0
	global_load_dwordx4 v[10:13], v80, s[18:19]
	s_add_u32 s18, s18, s3
	s_addc_u32 s19, s19, 0
	global_load_dwordx4 v[14:17], v80, s[18:19]
	s_mov_b64 exec, s[100:101]
	s_waitcnt vmcnt(0)
	ds_write_b32 v76, v2
	ds_write_b32 v76, v3 offset:4
	ds_write_b32 v76, v4 offset:8
	ds_write_b32 v76, v5 offset:12
	ds_write_b32 v76, v6 offset:4160
	ds_write_b32 v76, v7 offset:4164
	ds_write_b32 v76, v8 offset:4168
	ds_write_b32 v76, v9 offset:4172
	ds_write_b32 v76, v10 offset:8320
	ds_write_b32 v76, v11 offset:8324
	ds_write_b32 v76, v12 offset:8328
	ds_write_b32 v76, v13 offset:8332
	ds_write_b32 v76, v14 offset:12480
	ds_write_b32 v76, v15 offset:12484
	ds_write_b32 v76, v16 offset:12488
	ds_write_b32 v76, v17 offset:12492
	s_waitcnt lgkmcnt(0)
	s_barrier
	ds_read_b32 v50, v77
	ds_read_b32 v51, v77 offset:260
	ds_read_b32 v52, v77 offset:520
	ds_read_b32 v53, v77 offset:780
	ds_read_b32 v54, v77 offset:1040
	ds_read_b32 v55, v77 offset:1300
	ds_read_b32 v56, v77 offset:1560
	ds_read_b32 v57, v77 offset:1820
	ds_read_b32 v58, v77 offset:2080
	ds_read_b32 v59, v77 offset:2340
	ds_read_b32 v60, v77 offset:2600
	ds_read_b32 v61, v77 offset:2860
	ds_read_b32 v62, v77 offset:3120
	ds_read_b32 v63, v77 offset:3380
	ds_read_b32 v64, v77 offset:3640
	ds_read_b32 v65, v77 offset:3900
	s_add_i32 s15, s6, 7
	v_lshlrev_b32_e32 v82, s15, v78
	v_add_u32_e32 v82, v82, v79
	s_waitcnt lgkmcnt(0)
	v_cvt_pk_bf16_f32 v66, v50, v51
	v_cvt_pk_bf16_f32 v67, v52, v53
	v_cvt_pk_bf16_f32 v68, v54, v55
	v_cvt_pk_bf16_f32 v69, v56, v57
	v_cvt_pk_bf16_f32 v70, v58, v59
	v_cvt_pk_bf16_f32 v71, v60, v61
	v_cvt_pk_bf16_f32 v72, v62, v63
	v_cvt_pk_bf16_f32 v73, v64, v65
	global_store_dwordx4 v82, v[66:69], s[4:5]
	global_store_dwordx4 v82, v[70:73], s[4:5] offset:16
	s_barrier
	s_add_i32 s34, s34, 1
	s_mul_i32 s15, s34, s35
	s_cmp_lt_u32 s15, 0x1c80
	s_cbranch_scc1 .Lcvta_loop
	s_waitcnt vmcnt(0)
	s_branch .LBB0_842
